# XCD-aware tile order for the ffn-out GEMM: blocks of one XCD share 8 A row-blocks (cuts cross-XCD re-reads of the 46 MB activation)
# speedup vs baseline: 1.1127x; 1.0108x over previous
.LBB0_153:
	s_ashr_i32 s20, s47, 12
	s_add_i32 s24, s20, 1
	s_and_b64 s[20:21], s[12:13], exec
	s_cselect_b32 s20, 0, s24
	v_readlane_b32 s24, v255, 2
	v_readlane_b32 s25, v255, 3
	v_lshrrev_b32_e32 v0, 3, v108
	v_and_or_b32 v0, v0, 4, v111
	s_movk_i32 s25, 0x210
	s_waitcnt vmcnt(7)
	v_and_or_b32 v66, v108, 64, v110
	v_mul_lo_u32 v0, v0, s25
	v_lshl_add_u32 v0, v66, 2, v0
	ds_write2_b32 v0, v50, v34 offset1:32
	ds_write2_b32 v0, v51, v35 offset0:132 offset1:164
	v_add_u32_e32 v34, 0x400, v0
	ds_write2_b32 v34, v52, v36 offset0:8 offset1:40
	ds_write2_b32 v34, v53, v37 offset0:140 offset1:172
	v_add_u32_e32 v34, 0x1000, v0
	ds_write2_b32 v34, v54, v38 offset0:32 offset1:64
	ds_write2_b32 v34, v55, v39 offset0:164 offset1:196
	v_add_u32_e32 v34, 0x1400, v0
	ds_write2_b32 v34, v56, v40 offset0:40 offset1:72
	ds_write2_b32 v34, v57, v41 offset0:172 offset1:204
	v_add_u32_e32 v34, 0x2000, v0
	ds_write2_b32 v34, v58, v42 offset0:64 offset1:96
	ds_write2_b32 v34, v59, v43 offset0:196 offset1:228
	v_add_u32_e32 v34, 0x2400, v0
	ds_write2_b32 v34, v60, v44 offset0:72 offset1:104
	ds_write2_b32 v34, v61, v45 offset0:204 offset1:236
	v_add_u32_e32 v34, 0x3000, v0
	ds_write2_b32 v34, v62, v46 offset0:96 offset1:128
	v_add_u32_e32 v34, 0x3200, v0
	ds_write2_b32 v34, v63, v47 offset0:100 offset1:132
	v_add_u32_e32 v34, 0x3400, v0
	ds_write2_b32 v34, v64, v48 offset0:104 offset1:136
	v_add_u32_e32 v34, 0x3600, v0
	ds_write2_b32 v34, v65, v49 offset0:108 offset1:140
	v_add_u32_e32 v34, 0x4000, v0
	ds_write2_b32 v34, v18, v2 offset0:128 offset1:160
	v_add_u32_e32 v2, 0x4400, v0
	ds_write2_b32 v2, v19, v3 offset0:4 offset1:36
	ds_write2_b32 v2, v20, v4 offset0:136 offset1:168
	v_add_u32_e32 v2, 0x4800, v0
	ds_write2_b32 v2, v21, v5 offset0:12 offset1:44
	v_add_u32_e32 v2, 0x5000, v0
	ds_write2_b32 v2, v22, v6 offset0:160 offset1:192
	v_add_u32_e32 v2, 0x5400, v0
	ds_write2_b32 v2, v23, v7 offset0:36 offset1:68
	ds_write2_b32 v2, v24, v8 offset0:168 offset1:200
	v_add_u32_e32 v2, 0x5800, v0
	s_mul_i32 s21, s24, 3
	ds_write2_b32 v2, v25, v9 offset0:44 offset1:76
	v_add_u32_e32 v2, 0x6000, v0
	s_add_i32 s20, s20, s21
	ds_write2_b32 v2, v26, v10 offset0:192 offset1:224
	v_add_u32_e32 v2, 0x6400, v0
	v_readlane_b32 s52, v252, 4
	s_mul_hi_i32 s21, s20, 0x6000
	s_mulk_i32 s20, 0x6000
	ds_write2_b32 v2, v27, v11 offset0:68 offset1:100
	ds_write2_b32 v2, v28, v12 offset0:200 offset1:232
	v_add_u32_e32 v2, 0x6800, v0
	v_readlane_b32 s66, v252, 18
	ds_write2_b32 v2, v29, v13 offset0:76 offset1:108
	v_add_u32_e32 v2, 0x7200, v0
	v_readlane_b32 s67, v252, 19
	s_add_u32 s20, s66, s20
	ds_write2_b32 v2, v30, v14 offset0:96 offset1:128
	v_add_u32_e32 v2, 0x7400, v0
	s_addc_u32 s21, s67, s21
	s_lshl_b32 s24, s49, 2
	ds_write2_b32 v2, v31, v15 offset0:100 offset1:132
	v_add_u32_e32 v2, 0x7600, v0
	v_add_u32_e32 v0, 0x7800, v0
	v_and_b32_e32 v4, 0x7c, v109
	s_add_u32 s20, s20, s24
	ds_write2_b32 v0, v33, v17 offset0:108 offset1:140
	s_addc_u32 s21, s21, 0
	v_lshlrev_b32_e32 v0, 2, v4
	ds_write2_b32 v2, v32, v16 offset0:104 offset1:136
	v_ashrrev_i32_e32 v8, 5, v108
	v_lshl_add_u64 v[2:3], s[20:21], 0, v[0:1]
	s_mov_b32 s20, 0x4b05000
	v_add_lshl_u32 v5, v8, s47, 10
	v_add_co_u32_e32 v2, vcc, s20, v2
	v_or3_b32 v6, v4, s49, v5
	v_mov_b32_e32 v7, v1
	v_addc_co_u32_e32 v3, vcc, 0, v3, vcc
	s_waitcnt lgkmcnt(0)
	s_barrier
	v_lshl_add_u64 v[22:23], v[6:7], 2, s[28:29]
	global_load_dwordx4 v[2:5], v[2:3], off
	s_nop 0
	global_load_dwordx4 v[10:13], v[22:23], off
	v_mad_u64_u32 v[8:9], s[20:21], v8, s25, v[0:1]
	ds_read_b128 v[14:17], v8
	ds_read_b128 v[18:21], v8 offset:4224
	v_add_u32_e32 v0, 0x2000, v6
	v_lshl_add_u64 v[24:25], v[0:1], 2, s[28:29]
	v_add_u32_e32 v0, 0x4000, v6
	v_readlane_b32 s53, v252, 5
	v_readlane_b32 s54, v252, 6
	v_readlane_b32 s55, v252, 7
	v_readlane_b32 s56, v252, 8
	v_readlane_b32 s57, v252, 9
	v_readlane_b32 s58, v252, 10
	v_readlane_b32 s59, v252, 11
	v_readlane_b32 s60, v252, 12
	v_readlane_b32 s61, v252, 13
	v_readlane_b32 s62, v252, 14
	v_readlane_b32 s63, v252, 15
	v_readlane_b32 s64, v252, 16
	v_readlane_b32 s65, v252, 17
	s_waitcnt vmcnt(0) lgkmcnt(1)
	v_pk_fma_f32 v[10:11], v[2:3], v[14:15], v[10:11]
	v_pk_fma_f32 v[12:13], v[4:5], v[16:17], v[12:13]
	global_store_dwordx4 v[22:23], v[10:13], off
	global_load_dwordx4 v[10:13], v[24:25], off
	v_lshl_add_u64 v[22:23], v[0:1], 2, s[28:29]
	v_add_u32_e32 v0, 0x6000, v6
	s_waitcnt vmcnt(0) lgkmcnt(0)
	v_pk_fma_f32 v[10:11], v[2:3], v[18:19], v[10:11]
	v_pk_fma_f32 v[12:13], v[4:5], v[20:21], v[12:13]
	global_store_dwordx4 v[24:25], v[10:13], off
	global_load_dwordx4 v[10:13], v[22:23], off
	ds_read_b128 v[14:17], v8 offset:8448
	ds_read_b128 v[18:21], v8 offset:12672
	v_lshl_add_u64 v[24:25], v[0:1], 2, s[28:29]
	v_add_u32_e32 v0, 0x8000, v6
	s_waitcnt vmcnt(0) lgkmcnt(1)
	v_pk_fma_f32 v[10:11], v[2:3], v[14:15], v[10:11]
	v_pk_fma_f32 v[12:13], v[4:5], v[16:17], v[12:13]
	global_store_dwordx4 v[22:23], v[10:13], off
	global_load_dwordx4 v[10:13], v[24:25], off
	v_lshl_add_u64 v[22:23], v[0:1], 2, s[28:29]
	v_add_u32_e32 v0, 0xa000, v6
	s_waitcnt vmcnt(0) lgkmcnt(0)
	v_pk_fma_f32 v[10:11], v[2:3], v[18:19], v[10:11]
	v_pk_fma_f32 v[12:13], v[4:5], v[20:21], v[12:13]
	global_store_dwordx4 v[24:25], v[10:13], off
	global_load_dwordx4 v[10:13], v[22:23], off
	ds_read_b128 v[14:17], v8 offset:16896
	ds_read_b128 v[18:21], v8 offset:21120
	v_lshl_add_u64 v[24:25], v[0:1], 2, s[28:29]
	v_add_u32_e32 v0, 0xc000, v6
	s_waitcnt vmcnt(0) lgkmcnt(1)
	v_pk_fma_f32 v[10:11], v[2:3], v[14:15], v[10:11]
	v_pk_fma_f32 v[12:13], v[4:5], v[16:17], v[12:13]
	global_store_dwordx4 v[22:23], v[10:13], off
	global_load_dwordx4 v[10:13], v[24:25], off
	v_lshl_add_u64 v[22:23], v[0:1], 2, s[28:29]
	v_add_u32_e32 v0, 0xe000, v6
	s_waitcnt vmcnt(0) lgkmcnt(0)
	v_pk_fma_f32 v[10:11], v[2:3], v[18:19], v[10:11]
	v_pk_fma_f32 v[12:13], v[4:5], v[20:21], v[12:13]
	global_store_dwordx4 v[24:25], v[10:13], off
	global_load_dwordx4 v[10:13], v[22:23], off
	ds_read_b128 v[14:17], v8 offset:25344
	ds_read_b128 v[18:21], v8 offset:29568
	v_lshl_add_u64 v[24:25], v[0:1], 2, s[28:29]
	v_add_u32_e32 v0, 0x10000, v6
	s_waitcnt vmcnt(0) lgkmcnt(1)
	v_pk_fma_f32 v[10:11], v[2:3], v[14:15], v[10:11]
	v_pk_fma_f32 v[12:13], v[4:5], v[16:17], v[12:13]
	global_store_dwordx4 v[22:23], v[10:13], off
	global_load_dwordx4 v[10:13], v[24:25], off
	v_lshl_add_u64 v[22:23], v[0:1], 2, s[28:29]
	v_add_u32_e32 v0, 0x12000, v6
	s_waitcnt vmcnt(0) lgkmcnt(0)
	v_pk_fma_f32 v[10:11], v[2:3], v[18:19], v[10:11]
	v_pk_fma_f32 v[12:13], v[4:5], v[20:21], v[12:13]
	global_store_dwordx4 v[24:25], v[10:13], off
	global_load_dwordx4 v[10:13], v[22:23], off
	ds_read_b128 v[14:17], v8 offset:33792
	ds_read_b128 v[18:21], v8 offset:38016
	v_lshl_add_u64 v[24:25], v[0:1], 2, s[28:29]
	v_add_u32_e32 v0, 0x14000, v6
	s_waitcnt vmcnt(0) lgkmcnt(1)
	v_pk_fma_f32 v[10:11], v[2:3], v[14:15], v[10:11]
	v_pk_fma_f32 v[12:13], v[4:5], v[16:17], v[12:13]
	global_store_dwordx4 v[22:23], v[10:13], off
	global_load_dwordx4 v[10:13], v[24:25], off
	v_lshl_add_u64 v[22:23], v[0:1], 2, s[28:29]
	v_add_u32_e32 v0, 0x16000, v6
	s_waitcnt vmcnt(0) lgkmcnt(0)
	v_pk_fma_f32 v[10:11], v[2:3], v[18:19], v[10:11]
	v_pk_fma_f32 v[12:13], v[4:5], v[20:21], v[12:13]
	global_store_dwordx4 v[24:25], v[10:13], off
	global_load_dwordx4 v[10:13], v[22:23], off
	ds_read_b128 v[14:17], v8 offset:42240
	ds_read_b128 v[18:21], v8 offset:46464
	v_lshl_add_u64 v[24:25], v[0:1], 2, s[28:29]
	v_add_u32_e32 v0, 0x18000, v6
	s_waitcnt vmcnt(0) lgkmcnt(1)
	v_pk_fma_f32 v[10:11], v[2:3], v[14:15], v[10:11]
	v_pk_fma_f32 v[12:13], v[4:5], v[16:17], v[12:13]
	global_store_dwordx4 v[22:23], v[10:13], off
	global_load_dwordx4 v[10:13], v[24:25], off
	v_lshl_add_u64 v[22:23], v[0:1], 2, s[28:29]
	v_add_u32_e32 v0, 0x1a000, v6
	s_waitcnt vmcnt(0) lgkmcnt(0)
	v_pk_fma_f32 v[10:11], v[2:3], v[18:19], v[10:11]
	v_pk_fma_f32 v[12:13], v[4:5], v[20:21], v[12:13]
	global_store_dwordx4 v[24:25], v[10:13], off
	global_load_dwordx4 v[10:13], v[22:23], off
	ds_read_b128 v[14:17], v8 offset:50688
	ds_read_b128 v[18:21], v8 offset:54912
	v_lshl_add_u64 v[24:25], v[0:1], 2, s[28:29]
	v_add_u32_e32 v0, 0x1c000, v6
	s_waitcnt vmcnt(0) lgkmcnt(1)
	v_pk_fma_f32 v[10:11], v[2:3], v[14:15], v[10:11]
	v_pk_fma_f32 v[12:13], v[4:5], v[16:17], v[12:13]
	global_store_dwordx4 v[22:23], v[10:13], off
	global_load_dwordx4 v[10:13], v[24:25], off
	v_lshl_add_u64 v[22:23], v[0:1], 2, s[28:29]
	v_add_u32_e32 v0, 0x1e000, v6
	s_waitcnt vmcnt(0) lgkmcnt(0)
	v_pk_fma_f32 v[10:11], v[2:3], v[18:19], v[10:11]
	v_pk_fma_f32 v[12:13], v[4:5], v[20:21], v[12:13]
	global_store_dwordx4 v[24:25], v[10:13], off
	global_load_dwordx4 v[10:13], v[22:23], off
	ds_read_b128 v[14:17], v8 offset:59136
	ds_read_b128 v[18:21], v8 offset:63360
	v_lshl_add_u64 v[24:25], v[0:1], 2, s[28:29]
	s_waitcnt vmcnt(0) lgkmcnt(1)
	v_pk_fma_f32 v[6:7], v[2:3], v[14:15], v[10:11]
	v_pk_fma_f32 v[8:9], v[4:5], v[16:17], v[12:13]
	global_store_dwordx4 v[22:23], v[6:9], off
	global_load_dwordx4 v[6:9], v[24:25], off
	s_waitcnt vmcnt(0) lgkmcnt(0)
	v_pk_fma_f32 v[2:3], v[2:3], v[18:19], v[6:7]
	v_pk_fma_f32 v[4:5], v[4:5], v[20:21], v[8:9]
	global_store_dwordx4 v[24:25], v[2:5], off

.LBB0_157:
	s_andn2_b64 vcc, exec, s[20:21]
	s_cbranch_vccnz .LBB0_154
	s_and_b32 s98, s46, 7
	s_lshl_b32 s98, s98, 6
	s_lshr_b32 s99, s46, 3
	s_or_b32 s98, s98, s99
	s_lshl_b32 s21, s98, 7
	v_lshlrev_b32_e32 v0, 3, v108
	s_and_b32 s49, s21, 0x380
	v_ashrrev_i32_e32 v36, 3, v108
	v_and_b32_e32 v37, 56, v0
	v_add_u32_e32 v0, s49, v36
	s_movk_i32 s24, 0xb00
	s_lshl_b32 s20, s98, 4
	v_mul_lo_u32 v0, v0, s24
	s_and_b32 s47, s20, 0xffffff80
	v_or_b32_e32 v0, v0, v37
	s_waitcnt lgkmcnt(0)
	v_lshl_add_u64 v[2:3], v[0:1], 1, s[26:27]
	v_add_u32_e32 v0, s47, v36
	v_mul_lo_u32 v0, v0, s24
	v_or_b32_e32 v0, v0, v37
	v_lshl_add_u64 v[12:13], v[0:1], 1, s[90:91]
	v_mov_b32_e32 v74, v12
	v_mov_b32_e32 v75, v13
	v_mov_b32_e32 v72, v2
	v_mov_b32_e32 v73, v3
	v_mov_b32_e32 v104, 0x2c000
	v_mov_b32_e32 v105, 0
	v_lshl_add_u64 v[76:77], v[74:75], 0, v[104:105]
	v_lshl_add_u64 v[78:79], v[76:77], 0, v[104:105]
	v_lshl_add_u64 v[80:81], v[78:79], 0, v[104:105]
	v_lshl_add_u64 v[82:83], v[72:73], 0, v[104:105]
	v_lshl_add_u64 v[84:85], v[82:83], 0, v[104:105]
	v_lshl_add_u64 v[86:87], v[84:85], 0, v[104:105]
	v_and_b32_e32 v110, 31, v108
	v_ashrrev_i32_e32 v0, 1, v108
	v_and_b32_e32 v111, 0xffffffc0, v0
	v_readlane_b32 s52, v252, 4
	v_readlane_b32 s66, v252, 18
	v_readlane_b32 s67, v252, 19
	v_readlane_b32 s53, v252, 5
	v_readlane_b32 s54, v252, 6
	v_readlane_b32 s55, v252, 7
	v_readlane_b32 s56, v252, 8
	v_readlane_b32 s57, v252, 9
	v_readlane_b32 s58, v252, 10
	v_readlane_b32 s59, v252, 11
	v_readlane_b32 s60, v252, 12
	v_readlane_b32 s61, v252, 13
	v_readlane_b32 s62, v252, 14
	v_readlane_b32 s63, v252, 15
	v_readlane_b32 s64, v252, 16
	v_readlane_b32 s65, v252, 17
	s_barrier
	v_bfe_u32 v102, v108, 4, 3
	v_lshlrev_b32_e32 v102, 4, v102
	v_xor_b32_e32 v74, v102, v74
	v_xor_b32_e32 v76, v102, v76
	v_xor_b32_e32 v78, v102, v78
	v_xor_b32_e32 v80, v102, v80
	v_xor_b32_e32 v72, v102, v72
	v_xor_b32_e32 v82, v102, v82
	v_xor_b32_e32 v84, v102, v84
	v_xor_b32_e32 v86, v102, v86
	v_bfe_u32 v102, v108, 5, 1
	v_bfe_u32 v103, v108, 1, 3
	v_xor_b32_e32 v102, v102, v103
	v_lshlrev_b32_e32 v102, 4, v102
	v_lshrrev_b32_e32 v103, 1, v108
	v_and_b32_e32 v103, 64, v103
	v_and_b32_e32 v104, 31, v108
	v_or_b32_e32 v103, v103, v104
	v_lshl_or_b32 v94, v103, 7, v102
	v_and_b32_e32 v103, 0x5f, v108
	v_lshl_or_b32 v98, v103, 7, v102
	v_add_u32_e32 v98, 0x4000, v98
	v_xor_b32_e32 v95, 0x20, v94
	v_xor_b32_e32 v99, 0x20, v98
	v_xor_b32_e32 v96, 0x40, v94
	v_xor_b32_e32 v100, 0x40, v98
	v_xor_b32_e32 v97, 0x60, v94
	v_xor_b32_e32 v101, 0x60, v98
	v_mov_b32_e32 v214, 0x80
	v_mov_b32_e32 v215, 0
	s_lshl_b32 vcc_lo, s80, 4
	v_mov_b32_e32 v2, 0
	v_mov_b32_e32 v3, 0
	v_mov_b32_e32 v4, 0
	v_mov_b32_e32 v5, 0
	v_mov_b32_e32 v6, 0
	v_mov_b32_e32 v7, 0
	v_mov_b32_e32 v8, 0
	v_mov_b32_e32 v9, 0
	v_mov_b32_e32 v10, 0
	v_mov_b32_e32 v11, 0
	v_mov_b32_e32 v12, 0
	v_mov_b32_e32 v13, 0
	v_mov_b32_e32 v14, 0
	v_mov_b32_e32 v15, 0
	v_mov_b32_e32 v16, 0
	v_mov_b32_e32 v17, 0
	v_mov_b32_e32 v18, 0
	v_mov_b32_e32 v19, 0
	v_mov_b32_e32 v20, 0
	v_mov_b32_e32 v21, 0
	v_mov_b32_e32 v22, 0
	v_mov_b32_e32 v23, 0
	v_mov_b32_e32 v24, 0
	v_mov_b32_e32 v25, 0
	v_mov_b32_e32 v26, 0
	v_mov_b32_e32 v27, 0
	v_mov_b32_e32 v28, 0
	v_mov_b32_e32 v29, 0
	v_mov_b32_e32 v30, 0
	v_mov_b32_e32 v31, 0
	v_mov_b32_e32 v32, 0
	v_mov_b32_e32 v33, 0
	v_mov_b32_e32 v34, 0
	v_mov_b32_e32 v35, 0
	v_mov_b32_e32 v36, 0
	v_mov_b32_e32 v37, 0
	v_mov_b32_e32 v38, 0
	v_mov_b32_e32 v39, 0
	v_mov_b32_e32 v40, 0
	v_mov_b32_e32 v41, 0
	v_mov_b32_e32 v42, 0
	v_mov_b32_e32 v43, 0
	v_mov_b32_e32 v44, 0
	v_mov_b32_e32 v45, 0
	v_mov_b32_e32 v46, 0
	v_mov_b32_e32 v47, 0
	v_mov_b32_e32 v48, 0
	v_mov_b32_e32 v49, 0
	v_mov_b32_e32 v50, 0
	v_mov_b32_e32 v51, 0
	v_mov_b32_e32 v52, 0
	v_mov_b32_e32 v53, 0
	v_mov_b32_e32 v54, 0
	v_mov_b32_e32 v55, 0
	v_mov_b32_e32 v56, 0
	v_mov_b32_e32 v57, 0
	v_mov_b32_e32 v58, 0
	v_mov_b32_e32 v59, 0
	v_mov_b32_e32 v60, 0
	v_mov_b32_e32 v61, 0
	v_mov_b32_e32 v62, 0
	v_mov_b32_e32 v63, 0
	v_mov_b32_e32 v64, 0
	v_mov_b32_e32 v65, 0
	s_mov_b32 m0, vcc_lo
	s_nop 0
	global_load_lds_dwordx4 v[74:75], off
	s_add_u32 m0, vcc_lo, 0x1000
	s_nop 0
	global_load_lds_dwordx4 v[76:77], off
	s_add_u32 m0, vcc_lo, 0x2000
	s_nop 0
	global_load_lds_dwordx4 v[78:79], off
	s_add_u32 m0, vcc_lo, 0x3000
	s_nop 0
	global_load_lds_dwordx4 v[80:81], off
	s_add_u32 m0, vcc_lo, 0x4000
	s_nop 0
	global_load_lds_dwordx4 v[72:73], off
	s_add_u32 m0, vcc_lo, 0x5000
	s_nop 0
	global_load_lds_dwordx4 v[82:83], off
	s_add_u32 m0, vcc_lo, 0x6000
	s_nop 0
	global_load_lds_dwordx4 v[84:85], off
	s_add_u32 m0, vcc_lo, 0x7000
	s_nop 0
	global_load_lds_dwordx4 v[86:87], off
	v_lshl_add_u64 v[74:75], v[74:75], 0, v[214:215]
	v_lshl_add_u64 v[76:77], v[76:77], 0, v[214:215]
	v_lshl_add_u64 v[78:79], v[78:79], 0, v[214:215]
	v_lshl_add_u64 v[80:81], v[80:81], 0, v[214:215]
	v_lshl_add_u64 v[72:73], v[72:73], 0, v[214:215]
	v_lshl_add_u64 v[82:83], v[82:83], 0, v[214:215]
	v_lshl_add_u64 v[84:85], v[84:85], 0, v[214:215]
	v_lshl_add_u64 v[86:87], v[86:87], 0, v[214:215]
	s_add_u32 m0, vcc_lo, 0x8000
	s_nop 0
	global_load_lds_dwordx4 v[74:75], off
	s_add_u32 m0, vcc_lo, 0x9000
	s_nop 0
	global_load_lds_dwordx4 v[76:77], off
	s_add_u32 m0, vcc_lo, 0xa000
	s_nop 0
	global_load_lds_dwordx4 v[78:79], off
	s_add_u32 m0, vcc_lo, 0xb000
	s_nop 0
	global_load_lds_dwordx4 v[80:81], off
	s_add_u32 m0, vcc_lo, 0xc000
	s_nop 0
	global_load_lds_dwordx4 v[72:73], off
	s_add_u32 m0, vcc_lo, 0xd000
	s_nop 0
	global_load_lds_dwordx4 v[82:83], off
	s_add_u32 m0, vcc_lo, 0xe000
	s_nop 0
	global_load_lds_dwordx4 v[84:85], off
	s_add_u32 m0, vcc_lo, 0xf000
	s_nop 0
	global_load_lds_dwordx4 v[86:87], off
	v_lshl_add_u64 v[74:75], v[74:75], 0, v[214:215]
	v_lshl_add_u64 v[76:77], v[76:77], 0, v[214:215]
	v_lshl_add_u64 v[78:79], v[78:79], 0, v[214:215]
	v_lshl_add_u64 v[80:81], v[80:81], 0, v[214:215]
	v_lshl_add_u64 v[72:73], v[72:73], 0, v[214:215]
	v_lshl_add_u64 v[82:83], v[82:83], 0, v[214:215]
	v_lshl_add_u64 v[84:85], v[84:85], 0, v[214:215]
	v_lshl_add_u64 v[86:87], v[86:87], 0, v[214:215]
	s_mov_b32 vcc_hi, 21
	s_waitcnt vmcnt(8)
	s_barrier
	ds_read_b128 v[166:169], v94
	s_setprio 3
	ds_read_b128 v[170:173], v98
	ds_read_b128 v[174:177], v98 offset:4096
	ds_read_b128 v[178:181], v94 offset:4096
	ds_read_b128 v[182:185], v95
	ds_read_b128 v[188:191], v99
	ds_read_b128 v[192:195], v99 offset:4096
	ds_read_b128 v[206:209], v95 offset:4096
	s_waitcnt lgkmcnt(6)
	v_mfma_f32_32x32x16_bf16 v[50:65], v[166:169], v[170:173], v[50:65]
	ds_read_b128 v[236:239], v96
	s_waitcnt lgkmcnt(5)
	v_mfma_f32_32x32x16_bf16 v[18:33], v[178:181], v[170:173], v[18:33]
	ds_read_b128 v[240:243], v100
	v_mfma_f32_32x32x16_bf16 v[2:17], v[178:181], v[174:177], v[2:17]
	ds_read_b128 v[244:247], v100 offset:4096
	v_mfma_f32_32x32x16_bf16 v[34:49], v[166:169], v[174:177], v[34:49]
	ds_read_b128 v[248:251], v96 offset:4096
	s_waitcnt lgkmcnt(6)
	v_mfma_f32_32x32x16_bf16 v[50:65], v[182:185], v[188:191], v[50:65]
	ds_read_b128 v[126:129], v97
	s_waitcnt lgkmcnt(5)
	v_mfma_f32_32x32x16_bf16 v[18:33], v[206:209], v[188:191], v[18:33]
	ds_read_b128 v[130:133], v101
	v_mfma_f32_32x32x16_bf16 v[2:17], v[206:209], v[192:195], v[2:17]
	ds_read_b128 v[210:213], v101 offset:4096
	v_mfma_f32_32x32x16_bf16 v[34:49], v[182:185], v[192:195], v[34:49]
	ds_read_b128 v[222:225], v97 offset:4096
	s_waitcnt vmcnt(0) lgkmcnt(0)
	s_barrier
